# uvscan scan-unit prefix remainder: serialized 1-load-per-iteration loop replaced by up-to-15 batched loads then fma chain
# speedup vs baseline: 1.0054x; 1.0054x over previous
.LBB0_186:
	s_mov_b32 s25, s1
	s_lshl_b64 s[26:27], s[24:25], 12
	s_add_u32 s18, s18, s26
	s_addc_u32 s19, s19, s27
	s_add_u32 s18, s53, s18
	s_addc_u32 s19, s54, s19
	v_lshl_add_u64 v[4:5], v[2:3], 3, s[18:19]
	s_mov_b64 s[18:19], 0x1000
	s_sub_i32 s25, s17, s24
	global_load_dwordx2 v[108:109], v[4:5], off offset:-4
	s_cmp_eq_u32 s25, 1
	s_cbranch_scc1 .Lpfx_wait
	v_lshl_add_u64 v[4:5], v[4:5], 0, s[18:19]
	global_load_dwordx2 v[110:111], v[4:5], off offset:-4
	s_cmp_eq_u32 s25, 2
	s_cbranch_scc1 .Lpfx_wait
	v_lshl_add_u64 v[4:5], v[4:5], 0, s[18:19]
	global_load_dwordx2 v[112:113], v[4:5], off offset:-4
	s_cmp_eq_u32 s25, 3
	s_cbranch_scc1 .Lpfx_wait
	v_lshl_add_u64 v[4:5], v[4:5], 0, s[18:19]
	global_load_dwordx2 v[114:115], v[4:5], off offset:-4
	s_cmp_eq_u32 s25, 4
	s_cbranch_scc1 .Lpfx_wait
	v_lshl_add_u64 v[4:5], v[4:5], 0, s[18:19]
	global_load_dwordx2 v[116:117], v[4:5], off offset:-4
	s_cmp_eq_u32 s25, 5
	s_cbranch_scc1 .Lpfx_wait
	v_lshl_add_u64 v[4:5], v[4:5], 0, s[18:19]
	global_load_dwordx2 v[118:119], v[4:5], off offset:-4
	s_cmp_eq_u32 s25, 6
	s_cbranch_scc1 .Lpfx_wait
	v_lshl_add_u64 v[4:5], v[4:5], 0, s[18:19]
	global_load_dwordx2 v[120:121], v[4:5], off offset:-4
	s_cmp_eq_u32 s25, 7
	s_cbranch_scc1 .Lpfx_wait
	v_lshl_add_u64 v[4:5], v[4:5], 0, s[18:19]
	global_load_dwordx2 v[122:123], v[4:5], off offset:-4
	s_cmp_eq_u32 s25, 8
	s_cbranch_scc1 .Lpfx_wait
	v_lshl_add_u64 v[4:5], v[4:5], 0, s[18:19]
	global_load_dwordx2 v[124:125], v[4:5], off offset:-4
	s_cmp_eq_u32 s25, 9
	s_cbranch_scc1 .Lpfx_wait
	v_lshl_add_u64 v[4:5], v[4:5], 0, s[18:19]
	global_load_dwordx2 v[126:127], v[4:5], off offset:-4
	s_cmp_eq_u32 s25, 10
	s_cbranch_scc1 .Lpfx_wait
	v_lshl_add_u64 v[4:5], v[4:5], 0, s[18:19]
	global_load_dwordx2 v[128:129], v[4:5], off offset:-4
	s_cmp_eq_u32 s25, 11
	s_cbranch_scc1 .Lpfx_wait
	v_lshl_add_u64 v[4:5], v[4:5], 0, s[18:19]
	global_load_dwordx2 v[130:131], v[4:5], off offset:-4
	s_cmp_eq_u32 s25, 12
	s_cbranch_scc1 .Lpfx_wait
	v_lshl_add_u64 v[4:5], v[4:5], 0, s[18:19]
	global_load_dwordx2 v[132:133], v[4:5], off offset:-4
	s_cmp_eq_u32 s25, 13
	s_cbranch_scc1 .Lpfx_wait
	v_lshl_add_u64 v[4:5], v[4:5], 0, s[18:19]
	global_load_dwordx2 v[134:135], v[4:5], off offset:-4
	s_cmp_eq_u32 s25, 14
	s_cbranch_scc1 .Lpfx_wait
	v_lshl_add_u64 v[4:5], v[4:5], 0, s[18:19]
	global_load_dwordx2 v[136:137], v[4:5], off offset:-4
.Lpfx_wait:
	s_waitcnt vmcnt(0)
	v_fma_f32 v11, v11, v108, v109
	s_cmp_eq_u32 s25, 1
	s_cbranch_scc1 .Lpfx_done
	v_fma_f32 v11, v11, v110, v111
	s_cmp_eq_u32 s25, 2
	s_cbranch_scc1 .Lpfx_done
	v_fma_f32 v11, v11, v112, v113
	s_cmp_eq_u32 s25, 3
	s_cbranch_scc1 .Lpfx_done
	v_fma_f32 v11, v11, v114, v115
	s_cmp_eq_u32 s25, 4
	s_cbranch_scc1 .Lpfx_done
	v_fma_f32 v11, v11, v116, v117
	s_cmp_eq_u32 s25, 5
	s_cbranch_scc1 .Lpfx_done
	v_fma_f32 v11, v11, v118, v119
	s_cmp_eq_u32 s25, 6
	s_cbranch_scc1 .Lpfx_done
	v_fma_f32 v11, v11, v120, v121
	s_cmp_eq_u32 s25, 7
	s_cbranch_scc1 .Lpfx_done
	v_fma_f32 v11, v11, v122, v123
	s_cmp_eq_u32 s25, 8
	s_cbranch_scc1 .Lpfx_done
	v_fma_f32 v11, v11, v124, v125
	s_cmp_eq_u32 s25, 9
	s_cbranch_scc1 .Lpfx_done
	v_fma_f32 v11, v11, v126, v127
	s_cmp_eq_u32 s25, 10
	s_cbranch_scc1 .Lpfx_done
	v_fma_f32 v11, v11, v128, v129
	s_cmp_eq_u32 s25, 11
	s_cbranch_scc1 .Lpfx_done
	v_fma_f32 v11, v11, v130, v131
	s_cmp_eq_u32 s25, 12
	s_cbranch_scc1 .Lpfx_done
	v_fma_f32 v11, v11, v132, v133
	s_cmp_eq_u32 s25, 13
	s_cbranch_scc1 .Lpfx_done
	v_fma_f32 v11, v11, v134, v135
	s_cmp_eq_u32 s25, 14
	s_cbranch_scc1 .Lpfx_done
	v_fma_f32 v11, v11, v136, v137
.Lpfx_done:
.LBB0_188:
	s_cmp_lg_u32 s17, 63
	v_mov_b64_e32 v[4:5], 0
	s_cbranch_scc1 .LBB0_190
	v_readlane_b32 s18, v254, 7
	v_readlane_b32 s19, v254, 8
	s_load_dwordx2 s[18:19], s[18:19], 0x100
	s_add_i32 s17, s62, 0xffffff80
	s_lshr_b32 s24, s17, 6
	s_mov_b32 s25, s1
	s_waitcnt lgkmcnt(0)
	s_add_u32 s17, s18, s10
	s_addc_u32 s26, s19, s11
	s_lshl_b64 s[18:19], s[24:25], 11
	s_add_u32 s18, s17, s18
	s_addc_u32 s19, s26, s19
	v_lshl_add_u64 v[4:5], v[2:3], 2, s[18:19]
	s_mov_b64 s[18:19], 0x16880000
	v_lshl_add_u64 v[4:5], v[4:5], 0, s[18:19]
